# v004 + P8 SwiGLU stores widened to dwordx4 via permlane16_swap + attention A pass-2 Q/KV tiles requested at pass-1 loop exit
# speedup vs baseline: 1.0116x; 1.0022x over previous
.LBB0_360:
	s_waitcnt lgkmcnt(0)
	s_barrier
	global_load_dwordx4 v[112:115], v[128:129], off offset:128
	global_load_dwordx4 v[116:119], v[128:129], off offset:160
	global_load_dwordx4 v[120:123], v[128:129], off offset:192
	global_load_dwordx4 v[124:127], v[128:129], off offset:224
	s_lshl_b32 s68, s92, 3
	v_mov_b32_e32 v81, 0
	v_or_b32_e32 v80, s68, v172
	v_lshrrev_b32_e32 v82, 1, v80
	v_xor_b32_e32 v82, v82, v215
	v_lshlrev_b32_e32 v82, 3, v82
	v_and_b32_e32 v86, 56, v82
	v_mul_lo_u32 v80, v80, s42
	v_or_b32_e32 v82, s68, v184
	v_or_b32_e32 v80, v86, v80
	s_lshl_b32 s69, s92, 10
	v_mul_lo_u32 v83, v82, s42
	v_lshl_add_u64 v[88:89], v[80:81], 1, s[30:31]
	v_or_b32_e32 v82, v83, v194
	v_add_u32_e32 v84, v83, v195
	v_lshl_add_u64 v[88:89], v[88:89], 0, s[18:19]
	s_mov_b32 m0, s69
	s_lshl_b32 s70, s92, 11
	v_mov_b32_e32 v83, 0
	global_load_lds_dwordx4 v[88:89], off
	v_lshl_add_u64 v[88:89], v[82:83], 1, s[30:31]
	s_add_i32 m0, s70, 0x2000
	v_lshl_add_u64 v[88:89], v[88:89], 0, s[12:13]
	v_mov_b32_e32 v85, 0
	global_load_lds_dwordx4 v[88:89], off
	v_lshl_add_u64 v[88:89], v[84:85], 1, s[26:27]
	s_add_i32 m0, s70, 0x2400
	s_nop 0
	global_load_lds_dwordx4 v[88:89], off
	s_add_u32 s72, s26, 0x60000
	v_lshl_add_u64 v[92:93], v[80:81], 1, s[28:29]
	s_addc_u32 s73, s27, 0
	v_lshlrev_b64 v[82:83], 1, v[82:83]
	v_lshl_add_u64 v[94:95], v[92:93], 0, s[20:21]
	s_add_i32 m0, s69, 0x6000
	v_lshl_add_u64 v[90:91], s[72:73], 0, v[82:83]
	global_load_lds_dwordx4 v[94:95], off
	s_add_i32 m0, s70, 0x8000
	v_lshlrev_b64 v[84:85], 1, v[84:85]
	global_load_lds_dwordx4 v[90:91], off
	s_add_i32 m0, s70, 0x8400
	v_lshl_add_u64 v[88:89], s[72:73], 0, v[84:85]
	s_add_u32 s74, s26, 0xc0000
	global_load_lds_dwordx4 v[88:89], off
	s_addc_u32 s75, s27, 0
	v_lshl_add_u64 v[88:89], v[92:93], 0, s[22:23]
	s_add_i32 m0, s69, 0xc000
	v_lshl_add_u64 v[82:83], s[74:75], 0, v[82:83]
	global_load_lds_dwordx4 v[88:89], off
	s_add_i32 m0, s70, 0xe000
	v_lshl_add_u64 v[84:85], s[74:75], 0, v[84:85]
	global_load_lds_dwordx4 v[82:83], off
	s_add_i32 m0, s70, 0xe400
	s_nop 0
	global_load_lds_dwordx4 v[84:85], off
	v_and_b32_e32 v2, 64, v193
	v_xor_b32_e32 v0, 32, v193
	v_add_u32_e32 v2, 64, v2
	v_cmp_lt_i32_e32 vcc, v0, v2
	s_xor_b64 s[24:25], s[36:37], -1
	v_mov_b32_e32 v3, s58
	v_cndmask_b32_e32 v0, v193, v0, vcc
	v_lshlrev_b32_e32 v198, 2, v0
	ds_bpermute_b32 v0, v198, v150
	v_or_b32_e32 v2, s57, v178
	v_lshlrev_b64 v[2:3], 11, v[2:3]
	v_lshl_add_u64 v[2:3], s[90:91], 0, v[2:3]
	v_lshl_add_u64 v[2:3], v[2:3], 0, s[4:5]
	s_waitcnt lgkmcnt(0)
	v_add_f32_e32 v0, v150, v0
	v_div_scale_f32 v4, s[36:37], v0, v0, 1.0
	v_rcp_f32_e32 v5, v4
	v_readfirstlane_b32 s4, v215
	s_lshr_b32 s37, s4, 6
	s_lshl_b32 s4, s37, 3
	v_fma_f32 v6, -v4, v5, 1.0
	v_fmac_f32_e32 v5, v6, v5
	v_div_scale_f32 v6, vcc, 1.0, v0, 1.0
	v_mul_f32_e32 v7, v6, v5
	v_fma_f32 v8, -v4, v7, v6
	v_fmac_f32_e32 v7, v8, v5
	v_fma_f32 v4, -v4, v7, v6
	v_div_fmas_f32 v4, v4, v5, v7
	v_div_fixup_f32 v0, v4, v0, 1.0
	v_pk_mul_f32 v[4:5], v[64:65], v[0:1] op_sel_hi:[1,0]
	v_pk_mul_f32 v[6:7], v[66:67], v[0:1] op_sel_hi:[1,0]
	v_pk_mul_f32 v[8:9], v[68:69], v[0:1] op_sel_hi:[1,0]
	v_pk_mul_f32 v[10:11], v[70:71], v[0:1] op_sel_hi:[1,0]
	v_pk_mul_f32 v[12:13], v[72:73], v[0:1] op_sel_hi:[1,0]
	v_pk_mul_f32 v[14:15], v[74:75], v[0:1] op_sel_hi:[1,0]
	v_pk_mul_f32 v[64:65], v[76:77], v[0:1] op_sel_hi:[1,0]
	v_pk_mul_f32 v[66:67], v[78:79], v[0:1] op_sel_hi:[1,0]
	v_pk_mul_f32 v[48:49], v[0:1], v[48:49] op_sel_hi:[0,1]
	v_pk_mul_f32 v[50:51], v[0:1], v[50:51] op_sel_hi:[0,1]
	v_pk_mul_f32 v[52:53], v[0:1], v[52:53] op_sel_hi:[0,1]
	v_pk_mul_f32 v[54:55], v[0:1], v[54:55] op_sel_hi:[0,1]
	v_pk_mul_f32 v[56:57], v[0:1], v[56:57] op_sel_hi:[0,1]
	v_pk_mul_f32 v[58:59], v[0:1], v[58:59] op_sel_hi:[0,1]
	v_pk_mul_f32 v[60:61], v[0:1], v[60:61] op_sel_hi:[0,1]
	v_pk_mul_f32 v[62:63], v[0:1], v[62:63] op_sel_hi:[0,1]
	v_pk_mul_f32 v[32:33], v[0:1], v[32:33] op_sel_hi:[0,1]
	v_pk_mul_f32 v[34:35], v[0:1], v[34:35] op_sel_hi:[0,1]
	v_pk_mul_f32 v[36:37], v[0:1], v[36:37] op_sel_hi:[0,1]
	v_pk_mul_f32 v[38:39], v[0:1], v[38:39] op_sel_hi:[0,1]
	v_pk_mul_f32 v[40:41], v[0:1], v[40:41] op_sel_hi:[0,1]
	v_pk_mul_f32 v[42:43], v[0:1], v[42:43] op_sel_hi:[0,1]
	v_pk_mul_f32 v[44:45], v[0:1], v[44:45] op_sel_hi:[0,1]
	v_pk_mul_f32 v[46:47], v[0:1], v[46:47] op_sel_hi:[0,1]
	v_pk_mul_f32 v[16:17], v[0:1], v[16:17] op_sel_hi:[0,1]
	v_pk_mul_f32 v[18:19], v[0:1], v[18:19] op_sel_hi:[0,1]
	v_pk_mul_f32 v[20:21], v[0:1], v[20:21] op_sel_hi:[0,1]
	v_pk_mul_f32 v[22:23], v[0:1], v[22:23] op_sel_hi:[0,1]
	v_pk_mul_f32 v[24:25], v[0:1], v[24:25] op_sel_hi:[0,1]
	v_pk_mul_f32 v[26:27], v[0:1], v[26:27] op_sel_hi:[0,1]
	v_pk_mul_f32 v[28:29], v[0:1], v[28:29] op_sel_hi:[0,1]
	v_pk_mul_f32 v[30:31], v[0:1], v[30:31] op_sel_hi:[0,1]
	v_lshlrev_b32_e32 v0, 1, v181
	v_lshl_add_u64 v[146:147], v[2:3], 0, v[0:1]
	v_cvt_pk_bf16_f32 v2, v4, v5
	v_cvt_pk_bf16_f32 v3, v6, v7
	global_store_dwordx2 v[146:147], v[2:3], off
	v_cvt_pk_bf16_f32 v2, v8, v9
	v_cvt_pk_bf16_f32 v3, v10, v11
	global_store_dwordx2 v[146:147], v[2:3], off offset:16
	v_cvt_pk_bf16_f32 v2, v12, v13
	v_cvt_pk_bf16_f32 v3, v14, v15
	global_store_dwordx2 v[146:147], v[2:3], off offset:32
	v_cvt_pk_bf16_f32 v2, v64, v65
	v_cvt_pk_bf16_f32 v3, v66, v67
	global_store_dwordx2 v[146:147], v[2:3], off offset:48
	v_cvt_pk_bf16_f32 v2, v48, v49
	v_cvt_pk_bf16_f32 v3, v50, v51
	global_store_dwordx2 v[146:147], v[2:3], off offset:64
	v_cvt_pk_bf16_f32 v2, v52, v53
	v_cvt_pk_bf16_f32 v3, v54, v55
	global_store_dwordx2 v[146:147], v[2:3], off offset:80
	v_cvt_pk_bf16_f32 v2, v56, v57
	v_cvt_pk_bf16_f32 v3, v58, v59
	global_store_dwordx2 v[146:147], v[2:3], off offset:96
	v_cvt_pk_bf16_f32 v2, v60, v61
	v_cvt_pk_bf16_f32 v3, v62, v63
	global_store_dwordx2 v[146:147], v[2:3], off offset:112
	v_cvt_pk_bf16_f32 v2, v32, v33
	v_cvt_pk_bf16_f32 v3, v34, v35
	global_store_dwordx2 v[146:147], v[2:3], off offset:128
	v_cvt_pk_bf16_f32 v2, v36, v37
	v_cvt_pk_bf16_f32 v3, v38, v39
	global_store_dwordx2 v[146:147], v[2:3], off offset:144
	v_cvt_pk_bf16_f32 v2, v40, v41
	v_cvt_pk_bf16_f32 v3, v42, v43
	global_store_dwordx2 v[146:147], v[2:3], off offset:160
	v_cvt_pk_bf16_f32 v2, v44, v45
	v_cvt_pk_bf16_f32 v3, v46, v47
	global_store_dwordx2 v[146:147], v[2:3], off offset:176
	v_cvt_pk_bf16_f32 v2, v16, v17
	v_cvt_pk_bf16_f32 v3, v18, v19
	global_store_dwordx2 v[146:147], v[2:3], off offset:192
	v_cvt_pk_bf16_f32 v2, v20, v21
	v_cvt_pk_bf16_f32 v3, v22, v23
	global_store_dwordx2 v[146:147], v[2:3], off offset:208
	v_cvt_pk_bf16_f32 v2, v24, v25
	v_cvt_pk_bf16_f32 v3, v26, v27
	global_store_dwordx2 v[146:147], v[2:3], off offset:224
	v_cvt_pk_bf16_f32 v2, v28, v29
	v_cvt_pk_bf16_f32 v3, v30, v31
	global_store_dwordx2 v[146:147], v[2:3], off offset:240
	v_or_b32_e32 v0, s4, v172
	v_lshrrev_b32_e32 v2, 1, v0
	v_xor_b32_e32 v2, v2, v215
	v_lshlrev_b32_e32 v2, 3, v2
	v_and_b32_e32 v6, 56, v2
	v_mul_lo_u32 v0, v0, s42
	v_or_b32_e32 v2, s4, v184
	v_or_b32_e32 v0, v6, v0
	s_lshl_b32 s4, s37, 10
	v_mul_lo_u32 v3, v2, s42
	v_lshl_add_u64 v[8:9], v[0:1], 1, s[30:31]
	s_add_i32 s39, s4, 0
	v_or_b32_e32 v2, v3, v194
	v_add_u32_e32 v4, v3, v195
	s_waitcnt vmcnt(0)
	s_waitcnt vmcnt(0)
	v_lshl_add_u64 v[8:9], v[8:9], 0, s[18:19]
	s_mov_b32 m0, s39
	s_lshl_b32 s36, s37, 11
	v_mov_b32_e32 v3, v1
	s_add_i32 s38, s36, 0
	v_lshl_add_u64 v[8:9], v[2:3], 1, s[30:31]
	s_add_i32 m0, s38, 0x2000
	v_lshl_add_u64 v[8:9], v[8:9], 0, s[12:13]
	v_mov_b32_e32 v5, v1
	v_lshl_add_u64 v[8:9], v[4:5], 1, s[26:27]
	s_add_i32 m0, s38, 0x2400
	s_andn2_b64 vcc, exec, s[34:35]
	s_cbranch_vccnz .LBB0_340
	s_add_u32 s30, s26, 0x60000
	v_lshl_add_u64 v[12:13], v[0:1], 1, s[28:29]
	s_addc_u32 s31, s27, 0
	v_lshlrev_b64 v[2:3], 1, v[2:3]
	v_lshl_add_u64 v[14:15], v[12:13], 0, s[20:21]
	s_add_i32 m0, s39, 0x6000
	v_lshl_add_u64 v[10:11], s[30:31], 0, v[2:3]
	s_add_i32 m0, s38, 0x8000
	v_lshlrev_b64 v[4:5], 1, v[4:5]
	s_add_i32 m0, s38, 0x8400
	v_lshl_add_u64 v[8:9], s[30:31], 0, v[4:5]
	s_add_u32 s26, s26, 0xc0000
	s_addc_u32 s27, s27, 0
	v_lshl_add_u64 v[8:9], v[12:13], 0, s[22:23]
	s_add_i32 m0, s39, 0xc000
	v_lshl_add_u64 v[2:3], s[26:27], 0, v[2:3]
	s_add_i32 m0, s38, 0xe000
	v_lshl_add_u64 v[4:5], s[26:27], 0, v[4:5]
	s_add_i32 m0, s38, 0xe400
	s_mulk_i32 s37, 0x6000
	s_and_b32 s26, s54, 3
	s_lshl_b32 s30, s55, 2
	v_add_u32_e32 v0, s37, v196
	s_lshl_b32 s26, s26, 8
	v_lshl_add_u64 v[128:129], v[0:1], 1, v[138:139]
	s_add_u32 s26, s56, s26
	v_add_u32_e32 v0, s37, v197
	s_addc_u32 s27, 0, 0
	v_lshl_add_u64 v[130:131], v[0:1], 1, v[138:139]
	v_add3_u32 v0, v188, s37, v6
	v_mov_b32_e32 v14, v1
	v_mov_b32_e32 v15, v1
	s_add_u32 s26, s50, s26
	v_lshl_add_u64 v[148:149], v[0:1], 1, v[142:143]
	v_mov_b32_e32 v0, v1
	v_mov_b32_e32 v2, v1
	v_mov_b32_e32 v3, v1
	v_mov_b32_e32 v4, v1
	v_mov_b32_e32 v5, v1
	v_mov_b32_e32 v6, v1
	v_mov_b32_e32 v7, v1
	v_mov_b32_e32 v8, v1
	v_mov_b32_e32 v9, v1
	v_mov_b32_e32 v10, v1
	v_mov_b32_e32 v11, v1
	v_mov_b32_e32 v12, v1
	v_mov_b32_e32 v13, v1
	v_mov_b64_e32 v[78:79], v[14:15]
	v_mov_b64_e32 v[62:63], v[14:15]
	v_mov_b64_e32 v[46:47], v[14:15]
	v_mov_b64_e32 v[30:31], v[14:15]
	s_addc_u32 s27, s51, s27
	s_sub_i32 s31, 31, s30
	s_mov_b32 s34, 0
	v_mov_b32_e32 v154, 0
	v_mov_b32_e32 v150, 0xf149f2ca
	v_mov_b64_e32 v[76:77], v[12:13]
	v_mov_b64_e32 v[74:75], v[10:11]
	v_mov_b64_e32 v[72:73], v[8:9]
	v_mov_b64_e32 v[70:71], v[6:7]
	v_mov_b64_e32 v[68:69], v[4:5]
	v_mov_b64_e32 v[66:67], v[2:3]
	v_mov_b64_e32 v[64:65], v[0:1]
	v_mov_b64_e32 v[60:61], v[12:13]
	v_mov_b64_e32 v[58:59], v[10:11]
	v_mov_b64_e32 v[56:57], v[8:9]
	v_mov_b64_e32 v[54:55], v[6:7]
	v_mov_b64_e32 v[52:53], v[4:5]
	v_mov_b64_e32 v[50:51], v[2:3]
	v_mov_b64_e32 v[48:49], v[0:1]
	v_mov_b64_e32 v[44:45], v[12:13]
	v_mov_b64_e32 v[42:43], v[10:11]
	v_mov_b64_e32 v[40:41], v[8:9]
	v_mov_b64_e32 v[38:39], v[6:7]
	v_mov_b64_e32 v[36:37], v[4:5]
	v_mov_b64_e32 v[34:35], v[2:3]
	v_mov_b64_e32 v[32:33], v[0:1]
	v_mov_b64_e32 v[28:29], v[12:13]
	v_mov_b64_e32 v[26:27], v[10:11]
	v_mov_b64_e32 v[24:25], v[8:9]
	v_mov_b64_e32 v[22:23], v[6:7]
	v_mov_b64_e32 v[20:21], v[4:5]
	v_mov_b64_e32 v[18:19], v[2:3]
	v_mov_b64_e32 v[16:17], v[0:1]
	s_branch .LBB0_364

.LBB0_893:
	v_lshl_add_u32 v146, s26, 8, v154
	v_or_b32_e32 v152, 16, v146
	v_or_b32_e32 v150, 32, v146
	v_ashrrev_i32_e32 v147, 31, v146
	v_ashrrev_i32_e32 v153, 31, v152
	v_ashrrev_i32_e32 v151, 31, v150
	v_or_b32_e32 v148, 48, v146
	v_lshl_add_u64 v[144:145], v[146:147], 2, s[12:13]
	v_lshl_add_u64 v[162:163], v[152:153], 2, s[12:13]
	v_lshl_add_u64 v[164:165], v[150:151], 2, s[12:13]
	v_ashrrev_i32_e32 v149, 31, v148
	v_lshl_add_u64 v[166:167], v[148:149], 2, s[12:13]
	global_load_dword v168, v[144:145], off
	global_load_dword v178, v[162:163], off
	global_load_dword v179, v[164:165], off
	global_load_dword v180, v[166:167], off
	s_nop 0
	global_load_dword v164, v[144:145], off offset:512
	global_load_dword v162, v[144:145], off offset:576
	global_load_dword v153, v[144:145], off offset:640
	global_load_dword v149, v[144:145], off offset:704
	s_waitcnt vmcnt(0)
	v_lshl_or_b32 v147, s55, 8, v156
	v_mov_b64_e32 v[144:145], s[10:11]
	v_add_u32_e32 v165, 0x80, v146
	v_add_u32_e32 v163, 0x90, v146
	v_add_u32_e32 v161, 0xa0, v146
	v_add_u32_e32 v151, 0xb0, v146
	v_mad_i64_i32 v[166:167], s[28:29], v146, s54, v[144:145]
	v_ashrrev_i32_e32 v146, 1, v147
	v_ashrrev_i32_e32 v147, 31, v146
	v_lshlrev_b64 v[146:147], 1, v[146:147]
	v_lshl_add_u64 v[166:167], v[166:167], 0, v[146:147]
	s_andn2_b64 vcc, exec, s[2:3]
	s_mov_b64 s[2:3], -1
	s_waitcnt vmcnt(0)
	s_nop 0
	v_fmamk_f32 v168, v168, 0x3a800000, v160
	v_rsq_f32_e32 v168, v168
	s_nop 0
	v_pk_mul_f32 v[126:127], v[126:127], v[168:169] op_sel_hi:[1,0]
	v_pk_mul_f32 v[124:125], v[124:125], v[168:169] op_sel_hi:[1,0]
	v_pk_mul_f32 v[122:123], v[122:123], v[168:169] op_sel_hi:[1,0]
	v_pk_mul_f32 v[120:121], v[120:121], v[168:169] op_sel_hi:[1,0]
	v_pk_mul_f32 v[118:119], v[118:119], v[168:169] op_sel_hi:[1,0]
	v_pk_mul_f32 v[116:117], v[116:117], v[168:169] op_sel_hi:[1,0]
	v_pk_mul_f32 v[114:115], v[114:115], v[168:169] op_sel_hi:[1,0]
	v_pk_mul_f32 v[112:113], v[112:113], v[168:169] op_sel_hi:[1,0]
	v_mul_f32_e32 v170, 0xbfb8aa3b, v124
	v_mul_f32_e32 v171, 0xbfb8aa3b, v126
	v_mul_f32_e32 v172, 0xbfb8aa3b, v120
	v_mul_f32_e32 v173, 0xbfb8aa3b, v122
	v_mul_f32_e32 v174, 0xbfb8aa3b, v116
	v_mul_f32_e32 v175, 0xbfb8aa3b, v118
	v_mul_f32_e32 v176, 0xbfb8aa3b, v112
	v_mul_f32_e32 v177, 0xbfb8aa3b, v114
	v_mov_b32_e32 v168, v124
	v_mov_b32_e32 v169, v126
	v_mov_b32_e32 v126, v125
	v_mov_b32_e32 v124, v120
	v_mov_b32_e32 v125, v122
	v_mov_b32_e32 v122, v121
	v_mov_b32_e32 v120, v116
	v_mov_b32_e32 v121, v118
	v_mov_b32_e32 v118, v117
	v_mov_b32_e32 v116, v112
	v_mov_b32_e32 v117, v114
	v_exp_f32_e32 v112, v170
	v_exp_f32_e32 v114, v171
	v_exp_f32_e32 v170, v172
	v_exp_f32_e32 v171, v173
	v_exp_f32_e32 v172, v174
	v_exp_f32_e32 v173, v175
	v_exp_f32_e32 v174, v176
	v_exp_f32_e32 v175, v177
	v_add_f32_e32 v176, 1.0, v170
	v_add_f32_e32 v177, 1.0, v171
	v_add_f32_e32 v183, 1.0, v174
	v_add_f32_e32 v184, 1.0, v175
	v_add_f32_e32 v181, 1.0, v172
	v_add_f32_e32 v182, 1.0, v173
	v_rcp_f32_e32 v172, v176
	v_rcp_f32_e32 v173, v177
	v_rcp_f32_e32 v176, v183
	v_rcp_f32_e32 v177, v184
	v_add_f32_e32 v114, 1.0, v114
	v_add_f32_e32 v112, 1.0, v112
	v_rcp_f32_e32 v171, v114
	v_pk_mul_f32 v[116:117], v[116:117], v[176:177]
	v_mov_b32_e32 v114, v113
	v_rcp_f32_e32 v170, v112
	v_pk_mul_f32 v[112:113], v[114:115], v[116:117]
	v_fmamk_f32 v114, v178, 0x3a800000, v160
	v_rcp_f32_e32 v174, v181
	v_rcp_f32_e32 v175, v182
	v_rsq_f32_e32 v114, v114
	v_cvt_pk_bf16_f32 v191, v112, v113
	v_pk_mul_f32 v[120:121], v[120:121], v[174:175]
	v_pk_mul_f32 v[110:111], v[110:111], v[114:115] op_sel_hi:[1,0]
	v_pk_mul_f32 v[108:109], v[108:109], v[114:115] op_sel_hi:[1,0]
	v_pk_mul_f32 v[118:119], v[118:119], v[120:121]
	v_mul_f32_e32 v112, 0xbfb8aa3b, v108
	v_mul_f32_e32 v113, 0xbfb8aa3b, v110
	v_cvt_pk_bf16_f32 v190, v118, v119
	v_exp_f32_e32 v112, v112
	v_exp_f32_e32 v113, v113
	v_pk_mul_f32 v[106:107], v[106:107], v[114:115] op_sel_hi:[1,0]
	v_pk_mul_f32 v[104:105], v[104:105], v[114:115] op_sel_hi:[1,0]
	v_mov_b32_e32 v116, v108
	v_mov_b32_e32 v117, v110
	v_mul_f32_e32 v108, 0xbfb8aa3b, v104
	v_mul_f32_e32 v110, 0xbfb8aa3b, v106
	v_exp_f32_e32 v108, v108
	v_exp_f32_e32 v115, v110
	v_add_f32_e32 v112, 1.0, v112
	v_add_f32_e32 v113, 1.0, v113
	v_rcp_f32_e32 v112, v112
	v_rcp_f32_e32 v113, v113
	v_mov_b32_e32 v110, v109
	v_add_f32_e32 v108, 1.0, v108
	v_add_f32_e32 v109, 1.0, v115
	v_rcp_f32_e32 v108, v108
	v_rcp_f32_e32 v109, v109
	v_pk_mul_f32 v[112:113], v[116:117], v[112:113]
	v_pk_mul_f32 v[102:103], v[102:103], v[114:115] op_sel_hi:[1,0]
	v_pk_mul_f32 v[110:111], v[110:111], v[112:113]
	v_mov_b32_e32 v112, v104
	v_mov_b32_e32 v113, v106
	v_pk_mul_f32 v[108:109], v[112:113], v[108:109]
	v_mov_b32_e32 v106, v105
	v_pk_mul_f32 v[104:105], v[106:107], v[108:109]
	v_cvt_pk_bf16_f32 v188, v110, v111
	v_cvt_pk_bf16_f32 v189, v104, v105
	v_mad_i64_i32 v[104:105], s[28:29], v152, s54, v[144:145]
	v_lshl_add_u64 v[104:105], v[104:105], 0, v[146:147]
	v_pk_mul_f32 v[100:101], v[100:101], v[114:115] op_sel_hi:[1,0]
	v_mul_f32_e32 v106, 0xbfb8aa3b, v100
	v_mul_f32_e32 v107, 0xbfb8aa3b, v102
	v_exp_f32_e32 v106, v106
	v_exp_f32_e32 v107, v107
	v_pk_mul_f32 v[98:99], v[98:99], v[114:115] op_sel_hi:[1,0]
	v_pk_mul_f32 v[96:97], v[96:97], v[114:115] op_sel_hi:[1,0]
	v_add_f32_e32 v106, 1.0, v106
	v_add_f32_e32 v107, 1.0, v107
	v_rcp_f32_e32 v106, v106
	v_rcp_f32_e32 v107, v107
	v_mov_b32_e32 v108, v100
	v_mov_b32_e32 v109, v102
	v_mul_f32_e32 v100, 0xbfb8aa3b, v96
	v_mul_f32_e32 v102, 0xbfb8aa3b, v98
	v_pk_mul_f32 v[106:107], v[108:109], v[106:107]
	v_exp_f32_e32 v100, v100
	v_exp_f32_e32 v108, v102
	v_mov_b32_e32 v102, v101
	v_pk_mul_f32 v[102:103], v[102:103], v[106:107]
	v_add_f32_e32 v100, 1.0, v100
	v_add_f32_e32 v101, 1.0, v108
	v_rcp_f32_e32 v100, v100
	v_rcp_f32_e32 v101, v101
	v_mov_b32_e32 v106, v96
	v_mov_b32_e32 v107, v98
	v_mov_b32_e32 v98, v97
	v_pk_mul_f32 v[100:101], v[106:107], v[100:101]
	v_pk_mul_f32 v[168:169], v[168:169], v[170:171]
	v_pk_mul_f32 v[96:97], v[98:99], v[100:101]
	v_fmamk_f32 v98, v179, 0x3a800000, v160
	v_rsq_f32_e32 v98, v98
	v_cvt_pk_bf16_f32 v193, v96, v97
	v_cvt_pk_bf16_f32 v192, v102, v103
	v_pk_mul_f32 v[94:95], v[94:95], v[98:99] op_sel_hi:[1,0]
	v_pk_mul_f32 v[92:93], v[92:93], v[98:99] op_sel_hi:[1,0]
	v_mul_f32_e32 v97, 0xbfb8aa3b, v94
	v_mul_f32_e32 v96, 0xbfb8aa3b, v92
	v_exp_f32_e32 v96, v96
	v_exp_f32_e32 v97, v97
	v_pk_mul_f32 v[90:91], v[90:91], v[98:99] op_sel_hi:[1,0]
	v_pk_mul_f32 v[88:89], v[88:89], v[98:99] op_sel_hi:[1,0]
	v_mov_b32_e32 v100, v92
	v_mov_b32_e32 v101, v94
	v_mul_f32_e32 v92, 0xbfb8aa3b, v88
	v_mul_f32_e32 v94, 0xbfb8aa3b, v90
	v_exp_f32_e32 v92, v92
	v_exp_f32_e32 v99, v94
	v_add_f32_e32 v96, 1.0, v96
	v_add_f32_e32 v97, 1.0, v97
	v_rcp_f32_e32 v96, v96
	v_rcp_f32_e32 v97, v97
	v_mov_b32_e32 v94, v93
	v_add_f32_e32 v92, 1.0, v92
	v_add_f32_e32 v93, 1.0, v99
	v_rcp_f32_e32 v92, v92
	v_rcp_f32_e32 v93, v93
	v_pk_mul_f32 v[96:97], v[100:101], v[96:97]
	v_pk_mul_f32 v[86:87], v[86:87], v[98:99] op_sel_hi:[1,0]
	v_pk_mul_f32 v[94:95], v[94:95], v[96:97]
	v_mov_b32_e32 v96, v88
	v_mov_b32_e32 v97, v90
	v_pk_mul_f32 v[92:93], v[96:97], v[92:93]
	v_mov_b32_e32 v90, v89
	v_pk_mul_f32 v[88:89], v[90:91], v[92:93]
	v_cvt_pk_bf16_f32 v194, v94, v95
	v_cvt_pk_bf16_f32 v195, v88, v89
	v_mad_i64_i32 v[88:89], s[28:29], v150, s54, v[144:145]
	v_lshl_add_u64 v[88:89], v[88:89], 0, v[146:147]
	v_pk_mul_f32 v[84:85], v[84:85], v[98:99] op_sel_hi:[1,0]
	v_mul_f32_e32 v90, 0xbfb8aa3b, v84
	v_mul_f32_e32 v91, 0xbfb8aa3b, v86
	v_exp_f32_e32 v90, v90
	v_exp_f32_e32 v91, v91
	v_pk_mul_f32 v[82:83], v[82:83], v[98:99] op_sel_hi:[1,0]
	v_pk_mul_f32 v[80:81], v[80:81], v[98:99] op_sel_hi:[1,0]
	v_add_f32_e32 v90, 1.0, v90
	v_add_f32_e32 v91, 1.0, v91
	v_rcp_f32_e32 v90, v90
	v_rcp_f32_e32 v91, v91
	v_mov_b32_e32 v92, v84
	v_mov_b32_e32 v93, v86
	v_mul_f32_e32 v84, 0xbfb8aa3b, v80
	v_mul_f32_e32 v86, 0xbfb8aa3b, v82
	v_pk_mul_f32 v[90:91], v[92:93], v[90:91]
	v_exp_f32_e32 v84, v84
	v_exp_f32_e32 v92, v86
	v_mov_b32_e32 v86, v85
	v_pk_mul_f32 v[86:87], v[86:87], v[90:91]
	v_add_f32_e32 v84, 1.0, v84
	v_add_f32_e32 v85, 1.0, v92
	v_rcp_f32_e32 v84, v84
	v_rcp_f32_e32 v85, v85
	v_mov_b32_e32 v90, v80
	v_mov_b32_e32 v91, v82
	v_mov_b32_e32 v82, v81
	v_pk_mul_f32 v[84:85], v[90:91], v[84:85]
	v_pk_mul_f32 v[124:125], v[124:125], v[172:173]
	v_pk_mul_f32 v[80:81], v[82:83], v[84:85]
	v_fmamk_f32 v82, v180, 0x3a800000, v160
	v_rsq_f32_e32 v82, v82
	v_cvt_pk_bf16_f32 v199, v80, v81
	v_cvt_pk_bf16_f32 v198, v86, v87
	v_pk_mul_f32 v[78:79], v[78:79], v[82:83] op_sel_hi:[1,0]
	v_pk_mul_f32 v[76:77], v[76:77], v[82:83] op_sel_hi:[1,0]
	v_mul_f32_e32 v81, 0xbfb8aa3b, v78
	v_mul_f32_e32 v80, 0xbfb8aa3b, v76
	v_exp_f32_e32 v80, v80
	v_exp_f32_e32 v81, v81
	v_pk_mul_f32 v[74:75], v[74:75], v[82:83] op_sel_hi:[1,0]
	v_pk_mul_f32 v[72:73], v[72:73], v[82:83] op_sel_hi:[1,0]
	v_mov_b32_e32 v84, v76
	v_mov_b32_e32 v85, v78
	v_mul_f32_e32 v76, 0xbfb8aa3b, v72
	v_mul_f32_e32 v78, 0xbfb8aa3b, v74
	v_exp_f32_e32 v76, v76
	v_exp_f32_e32 v83, v78
	v_add_f32_e32 v80, 1.0, v80
	v_add_f32_e32 v81, 1.0, v81
	v_rcp_f32_e32 v80, v80
	v_rcp_f32_e32 v81, v81
	v_mov_b32_e32 v78, v77
	v_add_f32_e32 v76, 1.0, v76
	v_add_f32_e32 v77, 1.0, v83
	v_rcp_f32_e32 v76, v76
	v_rcp_f32_e32 v77, v77
	v_pk_mul_f32 v[80:81], v[84:85], v[80:81]
	v_pk_mul_f32 v[70:71], v[70:71], v[82:83] op_sel_hi:[1,0]
	v_pk_mul_f32 v[78:79], v[78:79], v[80:81]
	v_mov_b32_e32 v80, v72
	v_mov_b32_e32 v81, v74
	v_pk_mul_f32 v[76:77], v[80:81], v[76:77]
	v_mov_b32_e32 v74, v73
	v_pk_mul_f32 v[72:73], v[74:75], v[76:77]
	v_cvt_pk_bf16_f32 v196, v78, v79
	v_cvt_pk_bf16_f32 v197, v72, v73
	v_mad_i64_i32 v[72:73], s[28:29], v148, s54, v[144:145]
	v_lshl_add_u64 v[72:73], v[72:73], 0, v[146:147]
	v_pk_mul_f32 v[68:69], v[68:69], v[82:83] op_sel_hi:[1,0]
	v_mul_f32_e32 v74, 0xbfb8aa3b, v68
	v_mul_f32_e32 v75, 0xbfb8aa3b, v70
	v_exp_f32_e32 v74, v74
	v_exp_f32_e32 v75, v75
	v_pk_mul_f32 v[66:67], v[66:67], v[82:83] op_sel_hi:[1,0]
	v_pk_mul_f32 v[64:65], v[64:65], v[82:83] op_sel_hi:[1,0]
	v_add_f32_e32 v74, 1.0, v74
	v_add_f32_e32 v75, 1.0, v75
	v_rcp_f32_e32 v74, v74
	v_rcp_f32_e32 v75, v75
	v_mov_b32_e32 v76, v68
	v_mov_b32_e32 v77, v70
	v_mul_f32_e32 v68, 0xbfb8aa3b, v64
	v_mul_f32_e32 v70, 0xbfb8aa3b, v66
	v_pk_mul_f32 v[74:75], v[76:77], v[74:75]
	v_exp_f32_e32 v68, v68
	v_exp_f32_e32 v76, v70
	v_mov_b32_e32 v70, v69
	v_pk_mul_f32 v[70:71], v[70:71], v[74:75]
	v_add_f32_e32 v68, 1.0, v68
	v_add_f32_e32 v69, 1.0, v76
	v_rcp_f32_e32 v68, v68
	v_rcp_f32_e32 v69, v69
	v_mov_b32_e32 v74, v64
	v_mov_b32_e32 v75, v66
	v_mov_b32_e32 v66, v65
	v_pk_mul_f32 v[68:69], v[74:75], v[68:69]
	v_pk_mul_f32 v[126:127], v[126:127], v[168:169]
	v_pk_mul_f32 v[64:65], v[66:67], v[68:69]
	v_fmamk_f32 v66, v164, 0x3a800000, v160
	v_rsq_f32_e32 v66, v66
	v_cvt_pk_bf16_f32 v201, v64, v65
	v_cvt_pk_bf16_f32 v200, v70, v71
	v_pk_mul_f32 v[62:63], v[62:63], v[66:67] op_sel_hi:[1,0]
	v_pk_mul_f32 v[60:61], v[60:61], v[66:67] op_sel_hi:[1,0]
	v_mul_f32_e32 v65, 0xbfb8aa3b, v62
	v_mul_f32_e32 v64, 0xbfb8aa3b, v60
	v_exp_f32_e32 v64, v64
	v_exp_f32_e32 v65, v65
	v_pk_mul_f32 v[58:59], v[58:59], v[66:67] op_sel_hi:[1,0]
	v_pk_mul_f32 v[56:57], v[56:57], v[66:67] op_sel_hi:[1,0]
	v_mov_b32_e32 v68, v60
	v_mov_b32_e32 v69, v62
	v_mul_f32_e32 v60, 0xbfb8aa3b, v56
	v_mul_f32_e32 v62, 0xbfb8aa3b, v58
	v_exp_f32_e32 v60, v60
	v_exp_f32_e32 v67, v62
	v_add_f32_e32 v64, 1.0, v64
	v_add_f32_e32 v65, 1.0, v65
	v_rcp_f32_e32 v64, v64
	v_rcp_f32_e32 v65, v65
	v_mov_b32_e32 v62, v61
	v_add_f32_e32 v60, 1.0, v60
	v_add_f32_e32 v61, 1.0, v67
	v_rcp_f32_e32 v60, v60
	v_rcp_f32_e32 v61, v61
	v_pk_mul_f32 v[64:65], v[68:69], v[64:65]
	v_pk_mul_f32 v[54:55], v[54:55], v[66:67] op_sel_hi:[1,0]
	v_pk_mul_f32 v[62:63], v[62:63], v[64:65]
	v_mov_b32_e32 v64, v56
	v_mov_b32_e32 v65, v58
	v_pk_mul_f32 v[60:61], v[64:65], v[60:61]
	v_mov_b32_e32 v58, v57
	v_pk_mul_f32 v[56:57], v[58:59], v[60:61]
	v_cvt_pk_bf16_f32 v202, v62, v63
	v_cvt_pk_bf16_f32 v203, v56, v57
	v_mad_i64_i32 v[56:57], s[28:29], v165, s54, v[144:145]
	v_lshl_add_u64 v[56:57], v[56:57], 0, v[146:147]
	v_pk_mul_f32 v[52:53], v[52:53], v[66:67] op_sel_hi:[1,0]
	v_mul_f32_e32 v58, 0xbfb8aa3b, v52
	v_mul_f32_e32 v59, 0xbfb8aa3b, v54
	v_exp_f32_e32 v58, v58
	v_exp_f32_e32 v59, v59
	v_pk_mul_f32 v[50:51], v[50:51], v[66:67] op_sel_hi:[1,0]
	v_pk_mul_f32 v[48:49], v[48:49], v[66:67] op_sel_hi:[1,0]
	v_add_f32_e32 v58, 1.0, v58
	v_add_f32_e32 v59, 1.0, v59
	v_rcp_f32_e32 v58, v58
	v_rcp_f32_e32 v59, v59
	v_mov_b32_e32 v60, v52
	v_mov_b32_e32 v61, v54
	v_mul_f32_e32 v52, 0xbfb8aa3b, v48
	v_mul_f32_e32 v54, 0xbfb8aa3b, v50
	v_pk_mul_f32 v[58:59], v[60:61], v[58:59]
	v_exp_f32_e32 v52, v52
	v_exp_f32_e32 v60, v54
	v_mov_b32_e32 v54, v53
	v_pk_mul_f32 v[54:55], v[54:55], v[58:59]
	v_add_f32_e32 v52, 1.0, v52
	v_add_f32_e32 v53, 1.0, v60
	v_rcp_f32_e32 v52, v52
	v_rcp_f32_e32 v53, v53
	v_mov_b32_e32 v58, v48
	v_mov_b32_e32 v59, v50
	v_mov_b32_e32 v50, v49
	v_pk_mul_f32 v[52:53], v[58:59], v[52:53]
	v_pk_mul_f32 v[122:123], v[122:123], v[124:125]
	v_pk_mul_f32 v[48:49], v[50:51], v[52:53]
	v_fmamk_f32 v50, v162, 0x3a800000, v160
	v_rsq_f32_e32 v50, v50
	v_cvt_pk_bf16_f32 v207, v48, v49
	v_cvt_pk_bf16_f32 v206, v54, v55
	v_pk_mul_f32 v[46:47], v[46:47], v[50:51] op_sel_hi:[1,0]
	v_pk_mul_f32 v[44:45], v[44:45], v[50:51] op_sel_hi:[1,0]
	v_mul_f32_e32 v49, 0xbfb8aa3b, v46
	v_mul_f32_e32 v48, 0xbfb8aa3b, v44
	v_exp_f32_e32 v48, v48
	v_exp_f32_e32 v49, v49
	v_pk_mul_f32 v[42:43], v[42:43], v[50:51] op_sel_hi:[1,0]
	v_pk_mul_f32 v[40:41], v[40:41], v[50:51] op_sel_hi:[1,0]
	v_mov_b32_e32 v52, v44
	v_mov_b32_e32 v53, v46
	v_mul_f32_e32 v44, 0xbfb8aa3b, v40
	v_mul_f32_e32 v46, 0xbfb8aa3b, v42
	v_exp_f32_e32 v44, v44
	v_exp_f32_e32 v51, v46
	v_add_f32_e32 v48, 1.0, v48
	v_add_f32_e32 v49, 1.0, v49
	v_rcp_f32_e32 v48, v48
	v_rcp_f32_e32 v49, v49
	v_mov_b32_e32 v46, v45
	v_add_f32_e32 v44, 1.0, v44
	v_add_f32_e32 v45, 1.0, v51
	v_rcp_f32_e32 v44, v44
	v_rcp_f32_e32 v45, v45
	v_pk_mul_f32 v[48:49], v[52:53], v[48:49]
	v_pk_mul_f32 v[38:39], v[38:39], v[50:51] op_sel_hi:[1,0]
	v_pk_mul_f32 v[46:47], v[46:47], v[48:49]
	v_mov_b32_e32 v48, v40
	v_mov_b32_e32 v49, v42
	v_pk_mul_f32 v[44:45], v[48:49], v[44:45]
	v_mov_b32_e32 v42, v41
	v_pk_mul_f32 v[40:41], v[42:43], v[44:45]
	v_cvt_pk_bf16_f32 v204, v46, v47
	v_cvt_pk_bf16_f32 v205, v40, v41
	v_mad_i64_i32 v[40:41], s[28:29], v163, s54, v[144:145]
	v_lshl_add_u64 v[40:41], v[40:41], 0, v[146:147]
	v_pk_mul_f32 v[36:37], v[36:37], v[50:51] op_sel_hi:[1,0]
	v_mul_f32_e32 v42, 0xbfb8aa3b, v36
	v_mul_f32_e32 v43, 0xbfb8aa3b, v38
	v_exp_f32_e32 v42, v42
	v_exp_f32_e32 v43, v43
	v_pk_mul_f32 v[34:35], v[34:35], v[50:51] op_sel_hi:[1,0]
	v_pk_mul_f32 v[32:33], v[32:33], v[50:51] op_sel_hi:[1,0]
	v_add_f32_e32 v42, 1.0, v42
	v_add_f32_e32 v43, 1.0, v43
	v_rcp_f32_e32 v42, v42
	v_rcp_f32_e32 v43, v43
	v_mov_b32_e32 v44, v36
	v_mov_b32_e32 v45, v38
	v_mul_f32_e32 v36, 0xbfb8aa3b, v32
	v_mul_f32_e32 v38, 0xbfb8aa3b, v34
	v_pk_mul_f32 v[42:43], v[44:45], v[42:43]
	v_exp_f32_e32 v36, v36
	v_exp_f32_e32 v44, v38
	v_mov_b32_e32 v38, v37
	v_pk_mul_f32 v[38:39], v[38:39], v[42:43]
	v_add_f32_e32 v36, 1.0, v36
	v_add_f32_e32 v37, 1.0, v44
	v_rcp_f32_e32 v36, v36
	v_rcp_f32_e32 v37, v37
	v_mov_b32_e32 v42, v32
	v_mov_b32_e32 v43, v34
	v_mov_b32_e32 v34, v33
	v_pk_mul_f32 v[36:37], v[42:43], v[36:37]
	v_cvt_pk_bf16_f32 v186, v126, v127
	v_pk_mul_f32 v[32:33], v[34:35], v[36:37]
	v_fmamk_f32 v34, v153, 0x3a800000, v160
	v_rsq_f32_e32 v34, v34
	v_cvt_pk_bf16_f32 v209, v32, v33
	v_cvt_pk_bf16_f32 v208, v38, v39
	v_pk_mul_f32 v[30:31], v[30:31], v[34:35] op_sel_hi:[1,0]
	v_pk_mul_f32 v[28:29], v[28:29], v[34:35] op_sel_hi:[1,0]
	v_mul_f32_e32 v33, 0xbfb8aa3b, v30
	v_mul_f32_e32 v32, 0xbfb8aa3b, v28
	v_exp_f32_e32 v32, v32
	v_exp_f32_e32 v33, v33
	v_pk_mul_f32 v[26:27], v[26:27], v[34:35] op_sel_hi:[1,0]
	v_pk_mul_f32 v[24:25], v[24:25], v[34:35] op_sel_hi:[1,0]
	v_mov_b32_e32 v36, v28
	v_mov_b32_e32 v37, v30
	v_mul_f32_e32 v28, 0xbfb8aa3b, v24
	v_mul_f32_e32 v30, 0xbfb8aa3b, v26
	v_exp_f32_e32 v28, v28
	v_exp_f32_e32 v35, v30
	v_add_f32_e32 v32, 1.0, v32
	v_add_f32_e32 v33, 1.0, v33
	v_rcp_f32_e32 v32, v32
	v_rcp_f32_e32 v33, v33
	v_mov_b32_e32 v30, v29
	v_add_f32_e32 v28, 1.0, v28
	v_add_f32_e32 v29, 1.0, v35
	v_rcp_f32_e32 v28, v28
	v_rcp_f32_e32 v29, v29
	v_pk_mul_f32 v[32:33], v[36:37], v[32:33]
	v_pk_mul_f32 v[22:23], v[22:23], v[34:35] op_sel_hi:[1,0]
	v_pk_mul_f32 v[30:31], v[30:31], v[32:33]
	v_mov_b32_e32 v32, v24
	v_mov_b32_e32 v33, v26
	v_pk_mul_f32 v[28:29], v[32:33], v[28:29]
	v_mov_b32_e32 v26, v25
	v_pk_mul_f32 v[24:25], v[26:27], v[28:29]
	v_cvt_pk_bf16_f32 v210, v30, v31
	v_cvt_pk_bf16_f32 v211, v24, v25
	v_mad_i64_i32 v[24:25], s[28:29], v161, s54, v[144:145]
	v_lshl_add_u64 v[24:25], v[24:25], 0, v[146:147]
	v_pk_mul_f32 v[20:21], v[20:21], v[34:35] op_sel_hi:[1,0]
	v_mul_f32_e32 v26, 0xbfb8aa3b, v20
	v_mul_f32_e32 v27, 0xbfb8aa3b, v22
	v_exp_f32_e32 v26, v26
	v_exp_f32_e32 v27, v27
	v_pk_mul_f32 v[18:19], v[18:19], v[34:35] op_sel_hi:[1,0]
	v_pk_mul_f32 v[16:17], v[16:17], v[34:35] op_sel_hi:[1,0]
	v_add_f32_e32 v26, 1.0, v26
	v_add_f32_e32 v27, 1.0, v27
	v_rcp_f32_e32 v26, v26
	v_rcp_f32_e32 v27, v27
	v_mov_b32_e32 v28, v20
	v_mov_b32_e32 v29, v22
	v_mul_f32_e32 v20, 0xbfb8aa3b, v16
	v_mul_f32_e32 v22, 0xbfb8aa3b, v18
	v_pk_mul_f32 v[26:27], v[28:29], v[26:27]
	v_exp_f32_e32 v20, v20
	v_exp_f32_e32 v28, v22
	v_mov_b32_e32 v22, v21
	v_pk_mul_f32 v[22:23], v[22:23], v[26:27]
	v_add_f32_e32 v20, 1.0, v20
	v_add_f32_e32 v21, 1.0, v28
	v_rcp_f32_e32 v20, v20
	v_rcp_f32_e32 v21, v21
	v_mov_b32_e32 v26, v16
	v_mov_b32_e32 v27, v18
	v_mov_b32_e32 v18, v17
	v_pk_mul_f32 v[20:21], v[26:27], v[20:21]
	v_cvt_pk_bf16_f32 v187, v122, v123
	v_pk_mul_f32 v[16:17], v[18:19], v[20:21]
	v_fmamk_f32 v18, v149, 0x3a800000, v160
	v_rsq_f32_e32 v18, v18
	v_cvt_pk_bf16_f32 v217, v16, v17
	v_cvt_pk_bf16_f32 v216, v22, v23
	v_pk_mul_f32 v[14:15], v[14:15], v[18:19] op_sel_hi:[1,0]
	v_pk_mul_f32 v[12:13], v[12:13], v[18:19] op_sel_hi:[1,0]
	v_mul_f32_e32 v17, 0xbfb8aa3b, v14
	v_mul_f32_e32 v16, 0xbfb8aa3b, v12
	v_exp_f32_e32 v16, v16
	v_exp_f32_e32 v17, v17
	v_pk_mul_f32 v[10:11], v[10:11], v[18:19] op_sel_hi:[1,0]
	v_pk_mul_f32 v[8:9], v[8:9], v[18:19] op_sel_hi:[1,0]
	v_mov_b32_e32 v20, v12
	v_mov_b32_e32 v21, v14
	v_mul_f32_e32 v12, 0xbfb8aa3b, v8
	v_mul_f32_e32 v14, 0xbfb8aa3b, v10
	v_exp_f32_e32 v12, v12
	v_exp_f32_e32 v19, v14
	v_add_f32_e32 v16, 1.0, v16
	v_add_f32_e32 v17, 1.0, v17
	v_rcp_f32_e32 v16, v16
	v_rcp_f32_e32 v17, v17
	v_mov_b32_e32 v14, v13
	v_add_f32_e32 v12, 1.0, v12
	v_add_f32_e32 v13, 1.0, v19
	v_rcp_f32_e32 v12, v12
	v_rcp_f32_e32 v13, v13
	v_pk_mul_f32 v[16:17], v[20:21], v[16:17]
	v_pk_mul_f32 v[6:7], v[6:7], v[18:19] op_sel_hi:[1,0]
	v_pk_mul_f32 v[14:15], v[14:15], v[16:17]
	v_mov_b32_e32 v16, v8
	v_mov_b32_e32 v17, v10
	v_pk_mul_f32 v[12:13], v[16:17], v[12:13]
	v_mov_b32_e32 v10, v9
	v_pk_mul_f32 v[8:9], v[10:11], v[12:13]
	v_cvt_pk_bf16_f32 v212, v14, v15
	v_cvt_pk_bf16_f32 v213, v8, v9
	v_mad_i64_i32 v[8:9], s[28:29], v151, s54, v[144:145]
	v_lshl_add_u64 v[8:9], v[8:9], 0, v[146:147]
	v_pk_mul_f32 v[4:5], v[4:5], v[18:19] op_sel_hi:[1,0]
	v_mul_f32_e32 v10, 0xbfb8aa3b, v4
	v_mul_f32_e32 v11, 0xbfb8aa3b, v6
	v_exp_f32_e32 v10, v10
	v_exp_f32_e32 v11, v11
	v_pk_mul_f32 v[2:3], v[2:3], v[18:19] op_sel_hi:[1,0]
	v_pk_mul_f32 v[0:1], v[0:1], v[18:19] op_sel_hi:[1,0]
	v_add_f32_e32 v10, 1.0, v10
	v_add_f32_e32 v11, 1.0, v11
	v_rcp_f32_e32 v10, v10
	v_rcp_f32_e32 v11, v11
	v_mov_b32_e32 v12, v4
	v_mov_b32_e32 v13, v6
	v_mul_f32_e32 v4, 0xbfb8aa3b, v0
	v_mul_f32_e32 v6, 0xbfb8aa3b, v2
	v_pk_mul_f32 v[10:11], v[12:13], v[10:11]
	v_exp_f32_e32 v4, v4
	v_exp_f32_e32 v12, v6
	v_mov_b32_e32 v6, v5
	v_pk_mul_f32 v[6:7], v[6:7], v[10:11]
	v_add_f32_e32 v4, 1.0, v4
	v_add_f32_e32 v5, 1.0, v12
	v_rcp_f32_e32 v4, v4
	v_rcp_f32_e32 v5, v5
	v_mov_b32_e32 v10, v0
	v_mov_b32_e32 v11, v2
	v_mov_b32_e32 v2, v1
	v_pk_mul_f32 v[4:5], v[10:11], v[4:5]
	v_pk_mul_f32 v[0:1], v[2:3], v[4:5]
	v_cvt_pk_bf16_f32 v218, v6, v7
	v_cvt_pk_bf16_f32 v219, v0, v1
	v_lshrrev_b32_e32 v162, 4, v214
	v_and_b32_e32 v162, 1, v162
	v_mul_u32_u24_e32 v162, 0x15ff8, v162
	v_mov_b32_e32 v163, 0
	v_lshl_add_u64 v[164:165], v[166:167], 0, v[162:163]
	s_mov_b64 s[64:65], 0x2c000
	s_mov_b64 s[66:67], 0x84000
	v_permlane16_swap_b32_e32 v186, v188
	v_permlane16_swap_b32_e32 v187, v189
	global_store_dwordx4 v[164:165], v[186:189], off
	v_permlane16_swap_b32_e32 v190, v192
	v_permlane16_swap_b32_e32 v191, v193
	global_store_dwordx4 v[164:165], v[190:193], off offset:128
	v_lshl_add_u64 v[164:165], v[164:165], 0, s[64:65]
	v_permlane16_swap_b32_e32 v194, v196
	v_permlane16_swap_b32_e32 v195, v197
	global_store_dwordx4 v[164:165], v[194:197], off
	v_permlane16_swap_b32_e32 v198, v200
	v_permlane16_swap_b32_e32 v199, v201
	global_store_dwordx4 v[164:165], v[198:201], off offset:128
	v_lshl_add_u64 v[164:165], v[164:165], 0, s[66:67]
	v_permlane16_swap_b32_e32 v202, v204
	v_permlane16_swap_b32_e32 v203, v205
	global_store_dwordx4 v[164:165], v[202:205], off
	v_permlane16_swap_b32_e32 v206, v208
	v_permlane16_swap_b32_e32 v207, v209
	global_store_dwordx4 v[164:165], v[206:209], off offset:128
	v_lshl_add_u64 v[164:165], v[164:165], 0, s[64:65]
	v_permlane16_swap_b32_e32 v210, v212
	v_permlane16_swap_b32_e32 v211, v213
	global_store_dwordx4 v[164:165], v[210:213], off
	v_permlane16_swap_b32_e32 v216, v218
	v_permlane16_swap_b32_e32 v217, v219
	global_store_dwordx4 v[164:165], v[216:219], off offset:128
	s_cbranch_vccnz .LBB0_886
	s_andn2_b64 vcc, exec, s[4:5]
	s_cbranch_vccnz .LBB0_885
	s_barrier
	s_branch .LBB0_885
